# GEMM tile headers: accumulators zeroed with 64 v_mov_b64 instead of 128 v_mov_b32
# speedup vs baseline: 1.0027x; 1.0027x over previous
.LBB0_397:
	s_ashr_i32 s31, s30, 31
	s_lshl_b64 s[34:35], s[30:31], 19
	s_add_u32 s34, s68, s34
	s_addc_u32 s35, s69, s35
	s_and_b64 s[36:37], s[2:3], exec
	s_cselect_b32 s31, s35, s47
	s_cselect_b32 s45, s34, s46
	s_ashr_i32 s29, s28, 31
	s_lshl_b64 s[36:37], s[28:29], 19
	s_add_u32 s36, s60, s36
	s_addc_u32 s37, s61, s37
	s_and_b64 s[54:55], s[2:3], exec
	s_cselect_b32 s29, s37, s49
	s_cselect_b32 s78, s36, s48
	s_add_u32 s46, s46, 0x40080
	s_addc_u32 s47, s47, 0
	s_add_u32 s85, s48, 0x100
	v_mov_b64_e32 v[0:1], 0
	s_addc_u32 s86, s49, 0
	s_mov_b32 s87, -2
	v_mov_b64_e32 v[2:3], 0
	v_mov_b64_e32 v[4:5], 0
	v_mov_b64_e32 v[6:7], 0
	v_mov_b64_e32 v[8:9], 0
	v_mov_b64_e32 v[10:11], 0
	v_mov_b64_e32 v[12:13], 0
	v_mov_b64_e32 v[14:15], 0
	v_mov_b64_e32 v[16:17], 0
	v_mov_b64_e32 v[18:19], 0
	v_mov_b64_e32 v[20:21], 0
	v_mov_b64_e32 v[22:23], 0
	v_mov_b64_e32 v[24:25], 0
	v_mov_b64_e32 v[26:27], 0
	v_mov_b64_e32 v[28:29], 0
	v_mov_b64_e32 v[30:31], 0
	v_mov_b64_e32 v[32:33], 0
	v_mov_b64_e32 v[34:35], 0
	v_mov_b64_e32 v[36:37], 0
	v_mov_b64_e32 v[38:39], 0
	v_mov_b64_e32 v[40:41], 0
	v_mov_b64_e32 v[42:43], 0
	v_mov_b64_e32 v[44:45], 0
	v_mov_b64_e32 v[46:47], 0
	v_mov_b64_e32 v[48:49], 0
	v_mov_b64_e32 v[50:51], 0
	v_mov_b64_e32 v[52:53], 0
	v_mov_b64_e32 v[54:55], 0
	v_mov_b64_e32 v[56:57], 0
	v_mov_b64_e32 v[58:59], 0
	v_mov_b64_e32 v[60:61], 0
	v_mov_b64_e32 v[62:63], 0
	v_mov_b64_e32 v[64:65], 0
	v_mov_b64_e32 v[66:67], 0
	v_mov_b64_e32 v[68:69], 0
	v_mov_b64_e32 v[70:71], 0
	v_mov_b64_e32 v[72:73], 0
	v_mov_b64_e32 v[74:75], 0
	v_mov_b64_e32 v[76:77], 0
	v_mov_b64_e32 v[78:79], 0
	v_mov_b64_e32 v[80:81], 0
	v_mov_b64_e32 v[82:83], 0
	v_mov_b64_e32 v[84:85], 0
	v_mov_b64_e32 v[86:87], 0
	v_mov_b64_e32 v[88:89], 0
	v_mov_b64_e32 v[90:91], 0
	v_mov_b64_e32 v[92:93], 0
	v_mov_b64_e32 v[94:95], 0
	v_mov_b64_e32 v[96:97], 0
	v_mov_b64_e32 v[98:99], 0
	v_mov_b64_e32 v[100:101], 0
	v_mov_b64_e32 v[102:103], 0
	v_mov_b64_e32 v[104:105], 0
	v_mov_b64_e32 v[106:107], 0
	v_mov_b64_e32 v[108:109], 0
	v_mov_b64_e32 v[110:111], 0
	v_mov_b64_e32 v[112:113], 0
	v_mov_b64_e32 v[114:115], 0
	v_mov_b64_e32 v[116:117], 0
	v_mov_b64_e32 v[118:119], 0
	v_mov_b64_e32 v[120:121], 0
	v_mov_b64_e32 v[122:123], 0
	v_mov_b64_e32 v[124:125], 0
	v_mov_b64_e32 v[126:127], 0

.LBB0_524:
	s_ashr_i32 s25, s24, 31
	s_lshl_b64 s[26:27], s[24:25], 19
	s_add_u32 s26, s44, s26
	s_addc_u32 s27, s45, s27
	s_and_b64 s[28:29], s[2:3], exec
	s_cselect_b32 s25, s27, s31
	s_cselect_b32 s77, s26, s30
	s_ashr_i32 s23, s22, 31
	s_lshl_b64 s[28:29], s[22:23], 19
	s_add_u32 s28, s39, s28
	s_addc_u32 s29, s46, s29
	s_and_b64 s[36:37], s[2:3], exec
	s_cselect_b32 s23, s29, s35
	s_cselect_b32 s78, s28, s34
	s_add_u32 s30, s30, 0x40080
	s_addc_u32 s31, s31, 0
	s_add_u32 s79, s34, 0x100
	v_mov_b64_e32 v[0:1], 0
	s_addc_u32 s81, s35, 0
	s_mov_b32 s82, -2
	v_mov_b64_e32 v[2:3], 0
	v_mov_b64_e32 v[4:5], 0
	v_mov_b64_e32 v[6:7], 0
	v_mov_b64_e32 v[8:9], 0
	v_mov_b64_e32 v[10:11], 0
	v_mov_b64_e32 v[12:13], 0
	v_mov_b64_e32 v[14:15], 0
	v_mov_b64_e32 v[16:17], 0
	v_mov_b64_e32 v[18:19], 0
	v_mov_b64_e32 v[20:21], 0
	v_mov_b64_e32 v[22:23], 0
	v_mov_b64_e32 v[24:25], 0
	v_mov_b64_e32 v[26:27], 0
	v_mov_b64_e32 v[28:29], 0
	v_mov_b64_e32 v[30:31], 0
	v_mov_b64_e32 v[32:33], 0
	v_mov_b64_e32 v[34:35], 0
	v_mov_b64_e32 v[36:37], 0
	v_mov_b64_e32 v[38:39], 0
	v_mov_b64_e32 v[40:41], 0
	v_mov_b64_e32 v[42:43], 0
	v_mov_b64_e32 v[44:45], 0
	v_mov_b64_e32 v[46:47], 0
	v_mov_b64_e32 v[48:49], 0
	v_mov_b64_e32 v[50:51], 0
	v_mov_b64_e32 v[52:53], 0
	v_mov_b64_e32 v[54:55], 0
	v_mov_b64_e32 v[56:57], 0
	v_mov_b64_e32 v[58:59], 0
	v_mov_b64_e32 v[60:61], 0
	v_mov_b64_e32 v[62:63], 0
	v_mov_b64_e32 v[64:65], 0
	v_mov_b64_e32 v[66:67], 0
	v_mov_b64_e32 v[68:69], 0
	v_mov_b64_e32 v[70:71], 0
	v_mov_b64_e32 v[72:73], 0
	v_mov_b64_e32 v[74:75], 0
	v_mov_b64_e32 v[76:77], 0
	v_mov_b64_e32 v[78:79], 0
	v_mov_b64_e32 v[80:81], 0
	v_mov_b64_e32 v[82:83], 0
	v_mov_b64_e32 v[84:85], 0
	v_mov_b64_e32 v[86:87], 0
	v_mov_b64_e32 v[88:89], 0
	v_mov_b64_e32 v[90:91], 0
	v_mov_b64_e32 v[92:93], 0
	v_mov_b64_e32 v[94:95], 0
	v_mov_b64_e32 v[96:97], 0
	v_mov_b64_e32 v[98:99], 0
	v_mov_b64_e32 v[100:101], 0
	v_mov_b64_e32 v[102:103], 0
	v_mov_b64_e32 v[104:105], 0
	v_mov_b64_e32 v[106:107], 0
	v_mov_b64_e32 v[108:109], 0
	v_mov_b64_e32 v[110:111], 0
	v_mov_b64_e32 v[112:113], 0
	v_mov_b64_e32 v[114:115], 0
	v_mov_b64_e32 v[116:117], 0
	v_mov_b64_e32 v[118:119], 0
	v_mov_b64_e32 v[120:121], 0
	v_mov_b64_e32 v[122:123], 0
	v_mov_b64_e32 v[124:125], 0
	v_mov_b64_e32 v[126:127], 0

.LBB0_653:
	s_ashr_i32 s25, s24, 31
	s_lshl_b64 s[26:27], s[24:25], 19
	s_add_u32 s26, s44, s26
	s_addc_u32 s27, s45, s27
	s_and_b64 s[28:29], s[2:3], exec
	s_cselect_b32 s5, s27, s35
	s_cselect_b32 s25, s26, s34
	s_ashr_i32 s23, s22, 31
	s_lshl_b64 s[28:29], s[22:23], 19
	s_add_u32 s28, s38, s28
	s_addc_u32 s29, s39, s29
	s_and_b64 s[40:41], s[2:3], exec
	s_cselect_b32 s23, s29, s37
	s_cselect_b32 s76, s28, s36
	s_add_u32 s34, s34, 0x40080
	s_addc_u32 s35, s35, 0
	s_add_u32 s77, s36, 0x100
	v_mov_b64_e32 v[0:1], 0
	s_addc_u32 s78, s37, 0
	s_mov_b32 s79, -2
	v_mov_b64_e32 v[2:3], 0
	v_mov_b64_e32 v[4:5], 0
	v_mov_b64_e32 v[6:7], 0
	v_mov_b64_e32 v[8:9], 0
	v_mov_b64_e32 v[10:11], 0
	v_mov_b64_e32 v[12:13], 0
	v_mov_b64_e32 v[14:15], 0
	v_mov_b64_e32 v[16:17], 0
	v_mov_b64_e32 v[18:19], 0
	v_mov_b64_e32 v[20:21], 0
	v_mov_b64_e32 v[22:23], 0
	v_mov_b64_e32 v[24:25], 0
	v_mov_b64_e32 v[26:27], 0
	v_mov_b64_e32 v[28:29], 0
	v_mov_b64_e32 v[30:31], 0
	v_mov_b64_e32 v[32:33], 0
	v_mov_b64_e32 v[34:35], 0
	v_mov_b64_e32 v[36:37], 0
	v_mov_b64_e32 v[38:39], 0
	v_mov_b64_e32 v[40:41], 0
	v_mov_b64_e32 v[42:43], 0
	v_mov_b64_e32 v[44:45], 0
	v_mov_b64_e32 v[46:47], 0
	v_mov_b64_e32 v[48:49], 0
	v_mov_b64_e32 v[50:51], 0
	v_mov_b64_e32 v[52:53], 0
	v_mov_b64_e32 v[54:55], 0
	v_mov_b64_e32 v[56:57], 0
	v_mov_b64_e32 v[58:59], 0
	v_mov_b64_e32 v[60:61], 0
	v_mov_b64_e32 v[62:63], 0
	v_mov_b64_e32 v[64:65], 0
	v_mov_b64_e32 v[66:67], 0
	v_mov_b64_e32 v[68:69], 0
	v_mov_b64_e32 v[70:71], 0
	v_mov_b64_e32 v[72:73], 0
	v_mov_b64_e32 v[74:75], 0
	v_mov_b64_e32 v[76:77], 0
	v_mov_b64_e32 v[78:79], 0
	v_mov_b64_e32 v[80:81], 0
	v_mov_b64_e32 v[82:83], 0
	v_mov_b64_e32 v[84:85], 0
	v_mov_b64_e32 v[86:87], 0
	v_mov_b64_e32 v[88:89], 0
	v_mov_b64_e32 v[90:91], 0
	v_mov_b64_e32 v[92:93], 0
	v_mov_b64_e32 v[94:95], 0
	v_mov_b64_e32 v[96:97], 0
	v_mov_b64_e32 v[98:99], 0
	v_mov_b64_e32 v[100:101], 0
	v_mov_b64_e32 v[102:103], 0
	v_mov_b64_e32 v[104:105], 0
	v_mov_b64_e32 v[106:107], 0
	v_mov_b64_e32 v[108:109], 0
	v_mov_b64_e32 v[110:111], 0
	v_mov_b64_e32 v[112:113], 0
	v_mov_b64_e32 v[114:115], 0
	v_mov_b64_e32 v[116:117], 0
	v_mov_b64_e32 v[118:119], 0
	v_mov_b64_e32 v[120:121], 0
	v_mov_b64_e32 v[122:123], 0
	v_mov_b64_e32 v[124:125], 0
	v_mov_b64_e32 v[126:127], 0

.LBB0_866:
	s_ashr_i32 s23, s22, 31
	s_lshl_b64 s[24:25], s[22:23], 19
	s_add_u32 s24, s68, s24
	s_addc_u32 s25, s69, s25
	s_and_b64 s[26:27], s[2:3], exec
	s_cselect_b32 s23, s25, s29
	s_cselect_b32 s67, s24, s28
	s_ashr_i32 s21, s20, 31
	s_lshl_b64 s[26:27], s[20:21], 19
	s_add_u32 s26, s37, s26
	s_addc_u32 s27, s38, s27
	s_and_b64 s[34:35], s[2:3], exec
	s_cselect_b32 s21, s27, s31
	s_cselect_b32 s70, s26, s30
	s_add_u32 s28, s28, 0x40080
	s_addc_u32 s29, s29, 0
	s_add_u32 s71, s30, 0x100
	v_mov_b64_e32 v[0:1], 0
	s_addc_u32 s72, s31, 0
	s_mov_b32 s73, -2
	v_mov_b64_e32 v[2:3], 0
	v_mov_b64_e32 v[4:5], 0
	v_mov_b64_e32 v[6:7], 0
	v_mov_b64_e32 v[8:9], 0
	v_mov_b64_e32 v[10:11], 0
	v_mov_b64_e32 v[12:13], 0
	v_mov_b64_e32 v[14:15], 0
	v_mov_b64_e32 v[16:17], 0
	v_mov_b64_e32 v[18:19], 0
	v_mov_b64_e32 v[20:21], 0
	v_mov_b64_e32 v[22:23], 0
	v_mov_b64_e32 v[24:25], 0
	v_mov_b64_e32 v[26:27], 0
	v_mov_b64_e32 v[28:29], 0
	v_mov_b64_e32 v[30:31], 0
	v_mov_b64_e32 v[32:33], 0
	v_mov_b64_e32 v[34:35], 0
	v_mov_b64_e32 v[36:37], 0
	v_mov_b64_e32 v[38:39], 0
	v_mov_b64_e32 v[40:41], 0
	v_mov_b64_e32 v[42:43], 0
	v_mov_b64_e32 v[44:45], 0
	v_mov_b64_e32 v[46:47], 0
	v_mov_b64_e32 v[48:49], 0
	v_mov_b64_e32 v[50:51], 0
	v_mov_b64_e32 v[52:53], 0
	v_mov_b64_e32 v[54:55], 0
	v_mov_b64_e32 v[56:57], 0
	v_mov_b64_e32 v[58:59], 0
	v_mov_b64_e32 v[60:61], 0
	v_mov_b64_e32 v[62:63], 0
	v_mov_b64_e32 v[64:65], 0
	v_mov_b64_e32 v[66:67], 0
	v_mov_b64_e32 v[68:69], 0
	v_mov_b64_e32 v[70:71], 0
	v_mov_b64_e32 v[72:73], 0
	v_mov_b64_e32 v[74:75], 0
	v_mov_b64_e32 v[76:77], 0
	v_mov_b64_e32 v[78:79], 0
	v_mov_b64_e32 v[80:81], 0
	v_mov_b64_e32 v[82:83], 0
	v_mov_b64_e32 v[84:85], 0
	v_mov_b64_e32 v[86:87], 0
	v_mov_b64_e32 v[88:89], 0
	v_mov_b64_e32 v[90:91], 0
	v_mov_b64_e32 v[92:93], 0
	v_mov_b64_e32 v[94:95], 0
	v_mov_b64_e32 v[96:97], 0
	v_mov_b64_e32 v[98:99], 0
	v_mov_b64_e32 v[100:101], 0
	v_mov_b64_e32 v[102:103], 0
	v_mov_b64_e32 v[104:105], 0
	v_mov_b64_e32 v[106:107], 0
	v_mov_b64_e32 v[108:109], 0
	v_mov_b64_e32 v[110:111], 0
	v_mov_b64_e32 v[112:113], 0
	v_mov_b64_e32 v[114:115], 0
	v_mov_b64_e32 v[116:117], 0
	v_mov_b64_e32 v[118:119], 0
	v_mov_b64_e32 v[120:121], 0
	v_mov_b64_e32 v[122:123], 0
	v_mov_b64_e32 v[124:125], 0
	v_mov_b64_e32 v[126:127], 0
